# banded-attention unit prologue: bias-table load overlapped with the K/V DMA issue (counted vmcnt)
# speedup vs baseline: 1.0933x; 1.0060x over previous
.LBB0_393:
	s_or_b64 exec, exec, s[48:49]
	s_lshr_b32 s34, s30, 6
	v_sub_u32_e64 v0, s34, 2 clamp
	s_mov_b32 s8, 0x60000
	v_readfirstlane_b32 s1, v0
	v_mul_lo_u32 v0, s5, v0
	v_mad_u64_u32 v[8:9], s[36:37], v0, s8, v[8:9]
	v_mad_u64_u32 v[6:7], s[36:37], v0, s8, v[6:7]
	v_mad_u64_u32 v[4:5], s[36:37], v0, s8, v[4:5]
	s_lshl_b32 s14, s4, 9
	s_lshl_b64 s[36:37], s[14:15], 2
	v_readlane_b32 s4, v252, 38
	s_add_u32 s36, s4, s36
	v_readlane_b32 s4, v252, 39
	s_addc_u32 s37, s4, s37
	v_ashrrev_i32_e32 v3, 31, v2
	v_lshl_add_u64 v[16:17], v[2:3], 2, s[36:37]
	global_load_dword v3, v[16:17], off
	s_mul_i32 s14, s5, 0x60000
	v_mad_u64_u32 v[72:73], s[4:5], v0, s8, v[10:11]
	s_lshl_b32 s4, s31, 10
	v_lshl_add_u32 v15, v2, 2, 0
	s_add_i32 s5, s4, 0
	v_add_u32_e32 v15, 0x19000, v15
	s_mov_b32 m0, s5
	v_lshl_add_u64 v[10:11], v[6:7], 0, s[14:15]
	global_load_lds_dwordx4 v[4:5], off
	s_add_i32 m0, s5, 0x2000
	v_lshl_add_u64 v[4:5], v[4:5], 0, s[14:15]
	global_load_lds_dwordx4 v[6:7], off
	s_add_i32 m0, s5, 0x4000
	s_cmp_lt_u32 s7, 64
	global_load_lds_dwordx4 v[8:9], off
	v_lshl_add_u64 v[8:9], v[8:9], 0, s[14:15]
	s_cselect_b64 s[36:37], -1, 0
	s_cmp_gt_u32 s7, 63
	s_cbranch_scc1 .LBB0_395
	s_add_i32 m0, 0, 0x6000
	v_lshl_add_u64 v[6:7], v[72:73], 0, s[14:15]
	global_load_lds_dwordx4 v[72:73], off
	v_mov_b64_e32 v[72:73], v[6:7]
	v_mov_b64_e32 v[70:71], v[4:5]
	v_mov_b64_e32 v[68:69], v[2:3]
	v_mov_b64_e32 v[66:67], v[0:1]
	s_branch .LBB0_396

.LBB0_398:
	s_waitcnt vmcnt(6)
	ds_write_b32 v15, v3
	v_lshlrev_b32_e32 v125, 2, v13
	v_lshrrev_b32_e32 v0, 2, v2
	v_and_or_b32 v0, v0, 3, v125
	v_mul_u32_u24_e32 v142, 0xc0, v0
	v_and_b32_e32 v0, 16, v2
	v_lshlrev_b32_e32 v2, 2, v2
	v_and_or_b32 v0, v2, 12, v0
	v_cmp_gt_u32_e64 s[36:37], 32, v14
	v_lshlrev_b32_e32 v144, 1, v0
	v_mov_b32_e32 v14, v1
	v_cndmask_b32_e64 v0, 0, 1.0, s[36:37]
	v_cndmask_b32_e64 v143, v0, 0, s[16:17]
	v_lshlrev_b32_e32 v0, 2, v12
	v_lshl_or_b32 v0, s31, 7, v0
	v_sub_u32_e32 v0, v0, v124
	v_mov_b32_e32 v15, v1
	s_waitcnt vmcnt(0)
	v_mul_u32_u24_e32 v141, 0xd0, v12
	s_min_u32 s8, s34, 2
	v_add_u32_e32 v145, 0, v0
	v_mov_b32_e32 v226, 0
	v_mov_b32_e32 v227, 0
	v_mov_b32_e32 v228, 0
	v_mov_b32_e32 v229, 0
	v_mov_b32_e32 v230, 0
	v_mov_b32_e32 v231, 0
	v_mov_b32_e32 v232, 0
	v_mov_b32_e32 v233, 0
	v_mov_b32_e32 v234, 0
	v_mov_b32_e32 v235, 0
	v_mov_b32_e32 v236, 0
	v_mov_b32_e32 v237, 0
	v_mov_b32_e32 v238, 0
	v_mov_b32_e32 v239, 0
	v_mov_b32_e32 v240, 0
	v_mov_b32_e32 v241, 0
	v_mov_b32_e32 v242, 0
	v_mov_b32_e32 v243, 0
	v_mov_b32_e32 v244, 0
	v_mov_b32_e32 v245, 0
	v_mov_b32_e32 v246, 0
	v_mov_b32_e32 v247, 0
	v_mov_b32_e32 v248, 0
	v_mov_b32_e32 v249, 0
	v_mov_b32_e32 v166, 0
	v_mov_b32_e32 v167, 0
	v_mov_b32_e32 v168, 0
	v_mov_b32_e32 v169, 0
	v_mov_b32_e32 v170, 0
	v_mov_b32_e32 v171, 0
	v_mov_b32_e32 v172, 0
	v_mov_b32_e32 v173, 0
	v_mov_b32_e32 v0, v1
	v_mov_b32_e32 v2, v1
	v_mov_b32_e32 v3, v1
	v_mov_b32_e32 v4, v1
	v_mov_b32_e32 v5, v1
	v_mov_b32_e32 v6, v1
	v_mov_b32_e32 v7, v1
	v_mov_b32_e32 v8, v1
	v_mov_b32_e32 v9, v1
	v_mov_b32_e32 v10, v1
	v_mov_b32_e32 v11, v1
	v_mov_b32_e32 v12, v1
	v_mov_b32_e32 v13, v1
	v_mov_b64_e32 v[32:33], v[14:15]
	s_or_b32 s7, s34, 3
	s_or_b32 s5, s20, 31
	s_add_i32 s13, s20, s13
	s_lshl_b32 s20, s8, 8
	s_lshl_b32 s8, s8, 6
	v_mov_b64_e32 v[30:31], v[12:13]
	v_mov_b64_e32 v[28:29], v[10:11]
	v_mov_b64_e32 v[26:27], v[8:9]
	v_mov_b64_e32 v[24:25], v[6:7]
	v_mov_b64_e32 v[22:23], v[4:5]
	v_mov_b64_e32 v[20:21], v[2:3]
	v_mov_b64_e32 v[18:19], v[0:1]
	v_mov_b64_e32 v[16:17], v[14:15]
	s_sub_i32 s7, s7, s1
	s_sub_i32 s30, s30, s8
	s_mov_b32 s31, 0
	s_movk_i32 s34, 0xfc00
	v_mov_b64_e32 v[14:15], v[12:13]
	v_mov_b64_e32 v[12:13], v[10:11]
	v_mov_b64_e32 v[10:11], v[8:9]
	v_mov_b64_e32 v[8:9], v[6:7]
	v_mov_b64_e32 v[6:7], v[4:5]
	v_mov_b64_e32 v[4:5], v[2:3]
	v_mov_b64_e32 v[2:3], v[0:1]
	s_waitcnt vmcnt(0) lgkmcnt(0)
	s_barrier
	s_branch .LBB0_400
